# attention fused softmax: row sum via v_pk_add_f32, running-max v_max3 dropped (pair-end overflow guard on the row sum of exp2, reference moved to log2(sum) on the rare path)
# baseline (speedup 1.0000x reference)
; template <int TYPE>
; __device__ __forceinline__ void attn_item(const Ctx& a, int b, int h, int qt, LAS unsigned char* lds) {
;     ...
; #pragma unroll
;         for (int kk = 0; kk < NKK; ++kk)
; #pragma unroll
;             for (int sub = 0; sub < 2; ++sub)
;                 if (act[sub]) {
; #pragma unroll
;                     for (int kb = 0; kb < 2; ++kb) {
;                         bf16x8 ka = *(const LAS bf16x8*)(Kt + (sub * 64 + kb * 32 + l32) * KLD + kk * 16 + hb * 8);
;                         s[sub][kb] = __builtin_amdgcn_mfma_f32_32x32x16_bf16(ka, Q[kk], s[sub][kb], 0, 0, 0);
;                     }
;                 }
; #pragma unroll
;         for (int sub = 0; sub < 2; ++sub) {
;             if (!act[sub]) continue;
;             const int kt = kp * 2 + sub, kloc = kt - qt * 4;
;             if (kloc >= 0) {
; #pragma unroll
;                 for (int kb = 0; kb < 2; ++kb)
; #pragma unroll
;                     for (int r = 0; r < 16; ++r) { int kabs = kt * 64 + kb * 32 + (r >> 2) * 8 + hb * 4 + (r & 3); if (kabs > qrow) s[sub][kb][r] = -1e30f; }
;             } else if (TYPE == 1) {
;                 if (!((qmask >> (kt >> 2)) & 1u)) {
; #pragma unroll
;                     for (int kb = 0; kb < 2; ++kb)
; #pragma unroll
;                         for (int r = 0; r < 16; ++r) s[sub][kb][r] = -1e30f;
;                 }
;             }
;             float mx = -1e30f;
; #pragma unroll
;             for (int kb = 0; kb < 2; ++kb)
; #pragma unroll
;                 for (int r = 0; r < 16; ++r) mx = fmaxf(mx, s[sub][kb][r]);
;             mx = fmaxf(mx, __shfl_xor(mx, 32));
;             const float delta = mrun - mref;
;             const bool bump = (mx - delta) > 8.f;
;             const bool rare = __builtin_amdgcn_ballot_w64(bump || delta != 0.f) != 0ull;
;             float fpost = 1.f;
;             if (rare) {
;                 const float mnew = bump ? mref + mx : mrun;
;                 const float pre = __builtin_amdgcn_exp2f(delta);
;                 fpost = __builtin_amdgcn_exp2f(mref - mnew);
;                 mrun = mnew;
;                 lrun *= pre;
; #pragma unroll
;                 for (int db = 0; db < 2; ++db)
; #pragma unroll
;                     for (int r = 0; r < 16; ++r) oacc[db][r] *= pre;
;             }
;             float ps = 0.f;
; #pragma unroll
;             for (int kb = 0; kb < 2; ++kb)
; #pragma unroll
.Lat0_loop:
	s_add_u32 s8, s26, 2
	s_cmp_ge_u32 s8, s30
	s_cselect_b32 s57, 1, 0
	s_cmp_eq_u32 s57, 1
	s_cbranch_scc1 .Lat0_gen
	s_cmp_lg_u64 s[36:37], 0
	s_cbranch_scc1 .Lat0_gen
	v_mov_b32 v211, v0
	ds_read_b128 v[146:149], v190 offset:0
	ds_read_b128 v[150:153], v190 offset:6656
	ds_read_b128 v[154:157], v190 offset:32
	ds_read_b128 v[158:161], v190 offset:6688
	ds_read_b128 v[162:165], v190 offset:64
	ds_read_b128 v[166:169], v190 offset:6720
	s_waitcnt lgkmcnt(5)
	v_mfma_f32_32x32x16_bf16 v[48:63], v[146:149], v[112:115], 0
	ds_read_b128 v[170:173], v190 offset:96
	s_waitcnt lgkmcnt(5)
	v_mfma_f32_32x32x16_bf16 v[64:79], v[150:153], v[112:115], 0
	ds_read_b128 v[174:177], v190 offset:6752
	s_waitcnt lgkmcnt(5)
	v_mfma_f32_32x32x16_bf16 v[48:63], v[154:157], v[116:119], v[48:63]
	ds_read_b128 v[146:149], v190 offset:128
	s_waitcnt lgkmcnt(5)
	v_mfma_f32_32x32x16_bf16 v[64:79], v[158:161], v[116:119], v[64:79]
	ds_read_b128 v[150:153], v190 offset:6784
	s_waitcnt lgkmcnt(5)
	v_mfma_f32_32x32x16_bf16 v[48:63], v[162:165], v[120:123], v[48:63]
	ds_read_b128 v[154:157], v190 offset:160
	s_waitcnt lgkmcnt(5)
	v_mfma_f32_32x32x16_bf16 v[64:79], v[166:169], v[120:123], v[64:79]
	ds_read_b128 v[158:161], v190 offset:6816
	s_waitcnt lgkmcnt(5)
	v_mfma_f32_32x32x16_bf16 v[48:63], v[170:173], v[124:127], v[48:63]
	ds_read_b128 v[162:165], v190 offset:13312
	s_waitcnt lgkmcnt(5)
	v_mfma_f32_32x32x16_bf16 v[64:79], v[174:177], v[124:127], v[64:79]
	ds_read_b128 v[166:169], v190 offset:19968
	s_waitcnt lgkmcnt(5)
	v_mfma_f32_32x32x16_bf16 v[48:63], v[146:149], v[128:131], v[48:63]
	ds_read_b128 v[170:173], v190 offset:13344
	s_waitcnt lgkmcnt(5)
	v_mfma_f32_32x32x16_bf16 v[64:79], v[150:153], v[128:131], v[64:79]
	ds_read_b128 v[174:177], v190 offset:20000
	s_waitcnt lgkmcnt(5)
	v_mfma_f32_32x32x16_bf16 v[48:63], v[154:157], v[132:135], v[48:63]
	ds_read_b128 v[146:149], v190 offset:13376
	s_waitcnt lgkmcnt(5)
	v_mfma_f32_32x32x16_bf16 v[64:79], v[158:161], v[132:135], v[64:79]
	ds_read_b128 v[150:153], v190 offset:20032
	s_waitcnt vmcnt(0)
	s_waitcnt lgkmcnt(5)
	v_mfma_f32_32x32x16_bf16 v[80:95], v[162:165], v[112:115], 0
	ds_read_b128 v[154:157], v190 offset:13408
	s_nop 3
	v_exp_f32 v48, v48
	v_exp_f32 v49, v49
	v_exp_f32 v50, v50
	v_exp_f32 v51, v51
	v_mov_b32 v14, v48
	s_waitcnt lgkmcnt(5)
	v_mfma_f32_32x32x16_bf16 v[96:111], v[166:169], v[112:115], 0
	ds_write_b128 v193, v[2:5]
	ds_read_b128 v[158:161], v190 offset:20064
	v_mov_b32 v15, v49
	v_cvt_pk_bf16_f32 v48, v48, v49
	v_exp_f32 v52, v52
	v_exp_f32 v53, v53
	v_pk_add_f32 v[14:15], v[14:15], v[50:51]
	v_cvt_pk_bf16_f32 v49, v50, v51
	s_waitcnt lgkmcnt(6)
	v_mfma_f32_32x32x16_bf16 v[80:95], v[170:173], v[116:119], v[80:95]
	ds_read_b128 v[162:165], v190 offset:13440
	v_exp_f32 v54, v54
	v_exp_f32 v55, v55
	v_pk_add_f32 v[14:15], v[14:15], v[52:53]
	v_cvt_pk_bf16_f32 v50, v52, v53
	v_exp_f32 v56, v56
	v_exp_f32 v57, v57
	s_waitcnt lgkmcnt(6)
	v_mfma_f32_32x32x16_bf16 v[96:111], v[174:177], v[116:119], v[96:111]
	ds_write_b128 v193, v[10:13] offset:13312
	ds_read_b128 v[166:169], v190 offset:20096
	v_pk_add_f32 v[14:15], v[14:15], v[54:55]
	v_cvt_pk_bf16_f32 v51, v54, v55
	v_exp_f32 v58, v58
	v_exp_f32 v59, v59
	v_pk_add_f32 v[14:15], v[14:15], v[56:57]
	s_waitcnt lgkmcnt(7)
	v_mfma_f32_32x32x16_bf16 v[80:95], v[146:149], v[120:123], v[80:95]
	ds_read_b128 v[170:173], v190 offset:13472
	v_cvt_pk_bf16_f32 v52, v56, v57
	v_exp_f32 v60, v60
	v_exp_f32 v61, v61
	v_pk_add_f32 v[14:15], v[14:15], v[58:59]
	v_cvt_pk_bf16_f32 v53, v58, v59
	v_exp_f32 v62, v62
	s_waitcnt lgkmcnt(7)
	v_mfma_f32_32x32x16_bf16 v[96:111], v[150:153], v[120:123], v[96:111]
	ds_write_b128 v200, v[6:9]
	ds_read_b128 v[174:177], v190 offset:20128
	v_exp_f32 v63, v63
	v_pk_add_f32 v[14:15], v[14:15], v[60:61]
	v_cvt_pk_bf16_f32 v54, v60, v61
	v_pk_add_f32 v[14:15], v[14:15], v[62:63]
	v_cvt_pk_bf16_f32 v55, v62, v63
	v_exp_f32 v64, v64
	s_waitcnt lgkmcnt(8)
	v_mfma_f32_32x32x16_bf16 v[80:95], v[154:157], v[124:127], v[80:95]
	ds_read_b64_tr_b16 v[146:147], v191 offset:0
	ds_read_b64_tr_b16 v[148:149], v191 offset:1024
	v_exp_f32 v65, v65
	v_exp_f32 v66, v66
	v_exp_f32 v67, v67
	v_pk_add_f32 v[14:15], v[14:15], v[64:65]
	v_cvt_pk_bf16_f32 v64, v64, v65
	s_waitcnt lgkmcnt(8)
	v_mfma_f32_32x32x16_bf16 v[96:111], v[158:161], v[124:127], v[96:111]
	ds_write_b128 v200, v[136:139] offset:8192
	ds_read_b64_tr_b16 v[150:151], v192 offset:0
	ds_read_b64_tr_b16 v[152:153], v192 offset:1024
	v_exp_f32 v68, v68
	v_exp_f32 v69, v69
	v_pk_add_f32 v[14:15], v[14:15], v[66:67]
	v_cvt_pk_bf16_f32 v65, v66, v67
	v_exp_f32 v70, v70
	v_exp_f32 v71, v71
	s_waitcnt lgkmcnt(10)
	v_mfma_f32_32x32x16_bf16 v[80:95], v[162:165], v[128:131], v[80:95]
	ds_read_b64_tr_b16 v[154:155], v191 offset:2048
	ds_read_b64_tr_b16 v[156:157], v191 offset:3072
	v_pk_add_f32 v[14:15], v[14:15], v[68:69]
	v_cvt_pk_bf16_f32 v66, v68, v69
	v_exp_f32 v72, v72
	v_exp_f32 v73, v73
	v_pk_add_f32 v[14:15], v[14:15], v[70:71]
	v_cvt_pk_bf16_f32 v67, v70, v71
	s_waitcnt lgkmcnt(10)
	v_mfma_f32_32x32x16_bf16 v[96:111], v[166:169], v[128:131], v[96:111]
	ds_write_b128 v201, v[140:143]
	ds_read_b64_tr_b16 v[158:159], v192 offset:2048
	ds_read_b64_tr_b16 v[160:161], v192 offset:3072
	v_exp_f32 v74, v74
	v_exp_f32 v75, v75
	v_pk_add_f32 v[14:15], v[14:15], v[72:73]
	v_cvt_pk_bf16_f32 v68, v72, v73
	v_exp_f32 v76, v76
	s_waitcnt lgkmcnt(12)
	v_mfma_f32_32x32x16_bf16 v[80:95], v[170:173], v[132:135], v[80:95]
	ds_read_b64_tr_b16 v[162:163], v191 offset:4096
	ds_read_b64_tr_b16 v[164:165], v191 offset:5120
	v_exp_f32 v77, v77
	v_pk_add_f32 v[14:15], v[14:15], v[74:75]
	v_cvt_pk_bf16_f32 v69, v74, v75
	v_exp_f32 v78, v78
	v_exp_f32 v79, v79
	v_pk_add_f32 v[14:15], v[14:15], v[76:77]
	s_waitcnt lgkmcnt(12)
	v_mfma_f32_32x32x16_bf16 v[96:111], v[174:177], v[132:135], v[96:111]
	ds_read_b64_tr_b16 v[166:167], v192 offset:4096
	ds_read_b64_tr_b16 v[168:169], v192 offset:5120
	v_cvt_pk_bf16_f32 v70, v76, v77
	v_pk_add_f32 v[14:15], v[14:15], v[78:79]
	v_cvt_pk_bf16_f32 v71, v78, v79
	v_add_f32 v188, v14, v15
	v_add_f32 v206, v206, v188
	v_max_f32 v211, v211, v188
	s_cmp_eq_u32 s13, 2
	s_cselect_b32 s8, 0x1f800, 0
	s_sub_u32 s8, 0xa800, s8
	s_add_u32 s13, s13, 1
	s_cmp_eq_u32 s13, 3
	s_cselect_b32 s13, 0, s13
	s_waitcnt lgkmcnt(0)
	s_add_u32 s9, s26, 2
	s_cmp_lt_u32 s9, s30
	s_cbranch_scc0 .Lat0_mid1
	global_load_dwordx4 v[2:5], v184, s[52:53]
	global_load_dwordx4 v[6:9], v184, s[52:53] offset:128
	global_load_dwordx4 v[10:13], v185, s[52:53]
	global_load_dwordx4 v[136:139], v185, s[52:53] offset:128
	global_load_dwordx4 v[140:143], v186, s[54:55]
	s_add_u32 s52, s52, 0x70000
	s_addc_u32 s53, s53, 0
	s_add_u32 s54, s54, 0x10000
	s_addc_u32 s55, s55, 0
; template <int TYPE>
; __device__ __forceinline__ void attn_item(const Ctx& a, int b, int h, int qt, LAS unsigned char* lds) {
;     ...
;             float mx = -1e30f;
; #pragma unroll
;             for (int kb = 0; kb < 2; ++kb)
; #pragma unroll
;                 for (int r = 0; r < 16; ++r) mx = fmaxf(mx, s[sub][kb][r]);
;             mx = fmaxf(mx, __shfl_xor(mx, 32));
;             const float delta = mrun - mref;
;             const bool bump = (mx - delta) > 8.f;
;             const bool rare = __builtin_amdgcn_ballot_w64(bump || delta != 0.f) != 0ull;
;             float fpost = 1.f;
;             if (rare) {
;                 const float mnew = bump ? mref + mx : mrun;
;                 const float pre = __builtin_amdgcn_exp2f(delta);
;                 fpost = __builtin_amdgcn_exp2f(mref - mnew);
;                 mrun = mnew;
;                 lrun *= pre;
; #pragma unroll
;                 for (int db = 0; db < 2; ++db)
; #pragma unroll
;                     for (int r = 0; r < 16; ++r) oacc[db][r] *= pre;
;             }
;             float ps = 0.f;
; #pragma unroll
;             for (int kb = 0; kb < 2; ++kb)
; #pragma unroll
;                 for (int r = 0; r < 16; ++r) { float p = __builtin_amdgcn_exp2f(s[sub][kb][r]); s[sub][kb][r] = p; ps += p; }
;             lrun += ps;
; #pragma unroll
;             for (int kb = 0; kb < 2; ++kb)
; #pragma unroll
;                 for (int c = 0; c < 2; ++c) {
;                     bf16x8 pb = pack8(s[sub][kb], c);
; #pragma unroll
;                     for (int db = 0; db < 2; ++db)
;                         oacc[db] = __builtin_amdgcn_mfma_f32_32x32x16_bf16(lds_a2(VT + (db * 32 + l32) * VLD + sub * 64 + kb * 32 + c * 16 + hb * 4), pb, oacc[db], 0, 0, 0);
;                 }
;             if (rare) {
;                 lrun *= fpost;
; #pragma unroll
;                 for (int db = 0; db < 2; ++db)
; #pragma unroll
;                     for (int r = 0; r < 16; ++r) oacc[db][r] *= fpost;
;             }
;         }
.Lat0_mid1:
	v_add_u32 v193, s8, v193
	v_add_u32 v200, s8, v200
	v_add_u32 v201, s8, v201
	s_barrier
	s_nop 7
	v_mfma_f32_32x32x16_bf16 v[16:31], v[146:149], v[48:51], v[16:31]
	ds_read_b64_tr_b16 v[170:171], v191 offset:6144
	ds_read_b64_tr_b16 v[172:173], v191 offset:7168
	v_exp_f32 v80, v80
	v_exp_f32 v81, v81
	v_exp_f32 v82, v82
	v_exp_f32 v83, v83
	v_mov_b32 v14, v80
	v_mov_b32 v15, v81
	v_cvt_pk_bf16_f32 v80, v80, v81
	v_exp_f32 v84, v84
	v_mfma_f32_32x32x16_bf16 v[32:47], v[150:153], v[48:51], v[32:47]
	ds_read_b64_tr_b16 v[174:175], v192 offset:6144
	ds_read_b64_tr_b16 v[176:177], v192 offset:7168
	v_exp_f32 v85, v85
	v_pk_add_f32 v[14:15], v[14:15], v[82:83]
	v_cvt_pk_bf16_f32 v81, v82, v83
	v_exp_f32 v86, v86
	v_exp_f32 v87, v87
	v_pk_add_f32 v[14:15], v[14:15], v[84:85]
	v_cvt_pk_bf16_f32 v82, v84, v85
	v_exp_f32 v88, v88
	v_exp_f32 v89, v89
	v_mfma_f32_32x32x16_bf16 v[16:31], v[154:157], v[52:55], v[16:31]
	ds_read_b64_tr_b16 v[146:147], v191 offset:8192
	ds_read_b64_tr_b16 v[148:149], v191 offset:9216
	v_pk_add_f32 v[14:15], v[14:15], v[86:87]
	v_cvt_pk_bf16_f32 v83, v86, v87
	v_exp_f32 v90, v90
	v_exp_f32 v91, v91
	v_pk_add_f32 v[14:15], v[14:15], v[88:89]
	v_cvt_pk_bf16_f32 v84, v88, v89
	v_exp_f32 v92, v92
	v_exp_f32 v93, v93
	v_mfma_f32_32x32x16_bf16 v[32:47], v[158:161], v[52:55], v[32:47]
	ds_read_b64_tr_b16 v[150:151], v192 offset:8192
	ds_read_b64_tr_b16 v[152:153], v192 offset:9216
	v_pk_add_f32 v[14:15], v[14:15], v[90:91]
	v_cvt_pk_bf16_f32 v85, v90, v91
	v_exp_f32 v94, v94
	v_exp_f32 v95, v95
	v_pk_add_f32 v[14:15], v[14:15], v[92:93]
	v_cvt_pk_bf16_f32 v86, v92, v93
	v_pk_add_f32 v[14:15], v[14:15], v[94:95]
	v_cvt_pk_bf16_f32 v87, v94, v95
	v_exp_f32 v96, v96
	v_mfma_f32_32x32x16_bf16 v[16:31], v[162:165], v[64:67], v[16:31]
	ds_read_b64_tr_b16 v[154:155], v191 offset:10240
	ds_read_b64_tr_b16 v[156:157], v191 offset:11264
	v_exp_f32 v97, v97
	v_exp_f32 v98, v98
	v_exp_f32 v99, v99
	v_pk_add_f32 v[14:15], v[14:15], v[96:97]
	v_cvt_pk_bf16_f32 v96, v96, v97
	v_exp_f32 v100, v100
	v_exp_f32 v101, v101
	v_pk_add_f32 v[14:15], v[14:15], v[98:99]
	v_mfma_f32_32x32x16_bf16 v[32:47], v[166:169], v[64:67], v[32:47]
	ds_read_b64_tr_b16 v[158:159], v192 offset:10240
	ds_read_b64_tr_b16 v[160:161], v192 offset:11264
	v_cvt_pk_bf16_f32 v97, v98, v99
	v_exp_f32 v102, v102
	v_exp_f32 v103, v103
	v_pk_add_f32 v[14:15], v[14:15], v[100:101]
	v_cvt_pk_bf16_f32 v98, v100, v101
	v_exp_f32 v104, v104
	v_exp_f32 v105, v105
	v_pk_add_f32 v[14:15], v[14:15], v[102:103]
	v_cvt_pk_bf16_f32 v99, v102, v103
	s_waitcnt lgkmcnt(10)
	v_mfma_f32_32x32x16_bf16 v[16:31], v[170:173], v[68:71], v[16:31]
	ds_read_b64_tr_b16 v[162:163], v191 offset:12288
	ds_read_b64_tr_b16 v[164:165], v191 offset:13312
	v_exp_f32 v106, v106
	v_exp_f32 v107, v107
	v_pk_add_f32 v[14:15], v[14:15], v[104:105]
	v_cvt_pk_bf16_f32 v100, v104, v105
	v_exp_f32 v108, v108
	v_exp_f32 v109, v109
	v_pk_add_f32 v[14:15], v[14:15], v[106:107]
	v_cvt_pk_bf16_f32 v101, v106, v107
	s_waitcnt lgkmcnt(10)
	v_mfma_f32_32x32x16_bf16 v[32:47], v[174:177], v[68:71], v[32:47]
	ds_read_b64_tr_b16 v[166:167], v192 offset:12288
	ds_read_b64_tr_b16 v[168:169], v192 offset:13312
	v_exp_f32 v110, v110
	v_exp_f32 v111, v111
	v_pk_add_f32 v[14:15], v[14:15], v[108:109]
	v_cvt_pk_bf16_f32 v102, v108, v109
	v_pk_add_f32 v[14:15], v[14:15], v[110:111]
	v_cvt_pk_bf16_f32 v103, v110, v111
	v_add_f32 v188, v14, v15
	v_add_f32 v206, v206, v188
	v_max_f32 v211, v211, v188
	s_waitcnt lgkmcnt(10)
	v_mfma_f32_32x32x16_bf16 v[16:31], v[146:149], v[80:83], v[16:31]
	ds_read_b64_tr_b16 v[170:171], v191 offset:14336
	ds_read_b64_tr_b16 v[172:173], v191 offset:15360
	s_waitcnt lgkmcnt(10)
	v_mfma_f32_32x32x16_bf16 v[32:47], v[150:153], v[80:83], v[32:47]
	ds_read_b64_tr_b16 v[174:175], v192 offset:14336
	ds_read_b64_tr_b16 v[176:177], v192 offset:15360
	s_waitcnt lgkmcnt(10)
	v_mfma_f32_32x32x16_bf16 v[16:31], v[154:157], v[84:87], v[16:31]
	s_waitcnt lgkmcnt(8)
	v_mfma_f32_32x32x16_bf16 v[32:47], v[158:161], v[84:87], v[32:47]
	s_waitcnt lgkmcnt(6)
	v_mfma_f32_32x32x16_bf16 v[16:31], v[162:165], v[96:99], v[16:31]
	s_waitcnt lgkmcnt(4)
	v_mfma_f32_32x32x16_bf16 v[32:47], v[166:169], v[96:99], v[32:47]
	s_waitcnt lgkmcnt(2)
	v_mfma_f32_32x32x16_bf16 v[16:31], v[170:173], v[100:103], v[16:31]
	s_waitcnt lgkmcnt(0)
	v_mfma_f32_32x32x16_bf16 v[32:47], v[174:177], v[100:103], v[32:47]
	v_cmp_lt_f32 vcc, 0x47800000, v211
	s_cmp_lg_u64 vcc, 0
	s_cbranch_scc0 .Lat0_pairend
	v_mov_b32 v1, v211
	s_nop 1
	v_permlane32_swap_b32 v1, v211
	v_max_f32 v1, v1, v211
	v_cmp_lt_f32 vcc, 0x47800000, v1
	v_log_f32 v1, v1
	s_nop 0
	v_cndmask_b32 v14, v205, v1, vcc
	v_sub_f32 v15, v205, v14
	v_exp_f32 v15, v15
	v_mov_b32 v205, v14
	v_add_f32 v207, 0x41000000, v14
	v_mul_f32 v16, v16, v15
	v_mul_f32 v17, v17, v15
	v_mul_f32 v18, v18, v15
	v_mul_f32 v19, v19, v15
	v_mul_f32 v20, v20, v15
	v_mul_f32 v21, v21, v15
	v_mul_f32 v22, v22, v15
	v_mul_f32 v23, v23, v15
	v_mul_f32 v24, v24, v15
	v_mul_f32 v25, v25, v15
	v_mul_f32 v26, v26, v15
	v_mul_f32 v27, v27, v15
	v_mul_f32 v28, v28, v15
	v_mul_f32 v29, v29, v15
	v_mul_f32 v30, v30, v15
	v_mul_f32 v31, v31, v15
	v_mul_f32 v32, v32, v15
	v_mul_f32 v33, v33, v15
	v_mul_f32 v34, v34, v15
	v_mul_f32 v35, v35, v15
	v_mul_f32 v36, v36, v15
	v_mul_f32 v37, v37, v15
	v_mul_f32 v38, v38, v15
	v_mul_f32 v39, v39, v15
	v_mul_f32 v40, v40, v15
	v_mul_f32 v41, v41, v15
	v_mul_f32 v42, v42, v15
	v_mul_f32 v43, v43, v15
	v_mul_f32 v44, v44, v15
	v_mul_f32 v45, v45, v15
	v_mul_f32 v46, v46, v15
	v_mul_f32 v47, v47, v15
	v_mul_f32 v206, v206, v15
	v_cmp_neq_f32_e64 s[36:37], 0, v205
	s_branch .Lat0_pairend

; #define LAS __attribute__((address_space(3)))
; template <int TYPE>
; __device__ __forceinline__ void attn_item(const Ctx& a, int b, int h, int qt, LAS unsigned char* lds) {
;     ...
;         for (int sub = 0; sub < 2; ++sub) {
;             const int kloc = kp * 2 + sub - qt * 4;
;             act[sub] = (kloc < 0) || (kloc * 64 <= wv * 32 + 31);
;             if (TYPE == 1 && kloc < 0) act[sub] = __builtin_amdgcn_ballot_w64((qmask >> ((kp * 2 + sub) >> 2)) & 1u) != 0ull;
; #pragma unroll
;             for (int kb = 0; kb < 2; ++kb)
; #pragma unroll
;                 for (int r = 0; r < 16; ++r) s[sub][kb][r] = -mref;
;         }
; #pragma unroll
;         for (int kk = 0; kk < NKK; ++kk)
; #pragma unroll
;             for (int sub = 0; sub < 2; ++sub)
;                 if (act[sub]) {
; #pragma unroll
;                     for (int kb = 0; kb < 2; ++kb) {
;                         bf16x8 ka = *(const LAS bf16x8*)(Kt + (sub * 64 + kb * 32 + l32) * KLD + kk * 16 + hb * 8);
;                         s[sub][kb] = __builtin_amdgcn_mfma_f32_32x32x16_bf16(ka, Q[kk], s[sub][kb], 0, 0, 0);
;                     }
;                 }
;     ...
;             float ps = 0.f;
; #pragma unroll
;             for (int kb = 0; kb < 2; ++kb)
; #pragma unroll
;                 for (int r = 0; r < 16; ++r) { float p = __builtin_amdgcn_exp2f(s[sub][kb][r]); s[sub][kb][r] = p; ps += p; }
;             lrun += ps;
; #pragma unroll
;             for (int kb = 0; kb < 2; ++kb)
; #pragma unroll
;                 for (int c = 0; c < 2; ++c) {
;                     bf16x8 pb = pack8(s[sub][kb], c);
.Lat1_loop:
	s_add_u32 s8, s26, 2
	s_cmp_ge_u32 s8, s30
	s_cselect_b32 s57, 1, 0
	s_lshr_b32 s8, s26, 1
	v_lshrrev_b32 v1, s8, v209
	v_and_b32 v1, 1, v1
	v_sub_u32 v210, 0, v1
	v_cmp_ne_u32_e64 s[38:39], 0, v1
	s_cmp_eq_u32 s57, 1
	s_cbranch_scc1 .Lat1_gen
	s_cmp_eq_u64 s[38:39], 0
	s_cbranch_scc1 .Lat1_skip
	s_cmp_lg_u64 s[36:37], 0
	s_cbranch_scc1 .Lat1_gen
	v_mov_b32 v211, v0
	ds_read_b128 v[146:149], v190 offset:0
	ds_read_b128 v[150:153], v190 offset:4608
	ds_read_b128 v[154:157], v190 offset:32
	ds_read_b128 v[158:161], v190 offset:4640
	ds_read_b128 v[162:165], v190 offset:64
	ds_read_b128 v[166:169], v190 offset:4672
	s_waitcnt lgkmcnt(5)
	v_mfma_f32_32x32x16_bf16 v[48:63], v[146:149], v[112:115], 0
	ds_read_b128 v[170:173], v190 offset:96
	s_waitcnt lgkmcnt(5)
	v_mfma_f32_32x32x16_bf16 v[64:79], v[150:153], v[112:115], 0
	ds_read_b128 v[174:177], v190 offset:4704
	s_waitcnt lgkmcnt(5)
	v_mfma_f32_32x32x16_bf16 v[48:63], v[154:157], v[116:119], v[48:63]
	ds_read_b128 v[146:149], v190 offset:9216
	s_waitcnt lgkmcnt(5)
	v_mfma_f32_32x32x16_bf16 v[64:79], v[158:161], v[116:119], v[64:79]
	ds_read_b128 v[150:153], v190 offset:13824
	s_waitcnt lgkmcnt(5)
	v_mfma_f32_32x32x16_bf16 v[48:63], v[162:165], v[120:123], v[48:63]
	ds_read_b128 v[154:157], v190 offset:9248
	s_waitcnt lgkmcnt(5)
	v_mfma_f32_32x32x16_bf16 v[64:79], v[166:169], v[120:123], v[64:79]
	ds_read_b128 v[158:161], v190 offset:13856
	s_waitcnt lgkmcnt(5)
	v_mfma_f32_32x32x16_bf16 v[48:63], v[170:173], v[124:127], v[48:63]
	ds_read_b128 v[162:165], v190 offset:9280
	s_waitcnt lgkmcnt(5)
	v_mfma_f32_32x32x16_bf16 v[64:79], v[174:177], v[124:127], v[64:79]
	ds_read_b128 v[166:169], v190 offset:13888
	s_waitcnt vmcnt(0)
	s_waitcnt lgkmcnt(5)
	v_mfma_f32_32x32x16_bf16 v[80:95], v[146:149], v[112:115], 0
	ds_read_b128 v[170:173], v190 offset:9312
	s_nop 3
	v_exp_f32 v48, v48
	v_exp_f32 v49, v49
	v_exp_f32 v50, v50
	v_exp_f32 v51, v51
	v_mov_b32 v14, v48
	v_mov_b32 v15, v49
	v_cvt_pk_bf16_f32 v48, v48, v49
	v_and_b32 v48, v48, v210
	v_exp_f32 v52, v52
	v_exp_f32 v53, v53
	s_waitcnt lgkmcnt(5)
	v_mfma_f32_32x32x16_bf16 v[96:111], v[150:153], v[112:115], 0
	ds_write_b128 v193, v[2:5]
	ds_read_b128 v[174:177], v190 offset:13920
	v_pk_add_f32 v[14:15], v[14:15], v[50:51]
	v_cvt_pk_bf16_f32 v49, v50, v51
	v_and_b32 v49, v49, v210
	v_exp_f32 v54, v54
	v_exp_f32 v55, v55
	v_pk_add_f32 v[14:15], v[14:15], v[52:53]
	v_cvt_pk_bf16_f32 v50, v52, v53
	v_and_b32 v50, v50, v210
	v_exp_f32 v56, v56
	v_exp_f32 v57, v57
	v_pk_add_f32 v[14:15], v[14:15], v[54:55]
	s_waitcnt lgkmcnt(6)
	v_mfma_f32_32x32x16_bf16 v[80:95], v[154:157], v[116:119], v[80:95]
	ds_read_b64_tr_b16 v[146:147], v191 offset:0
	ds_read_b64_tr_b16 v[148:149], v191 offset:1024
	v_cvt_pk_bf16_f32 v51, v54, v55
	v_and_b32 v51, v51, v210
	v_exp_f32 v58, v58
	v_exp_f32 v59, v59
	v_pk_add_f32 v[14:15], v[14:15], v[56:57]
	v_cvt_pk_bf16_f32 v52, v56, v57
	v_and_b32 v52, v52, v210
	v_exp_f32 v60, v60
	v_exp_f32 v61, v61
	v_pk_add_f32 v[14:15], v[14:15], v[58:59]
	s_waitcnt lgkmcnt(7)
	v_mfma_f32_32x32x16_bf16 v[96:111], v[158:161], v[116:119], v[96:111]
	ds_write_b128 v193, v[10:13] offset:9216
	ds_read_b64_tr_b16 v[150:151], v192 offset:0
	ds_read_b64_tr_b16 v[152:153], v192 offset:1024
	v_cvt_pk_bf16_f32 v53, v58, v59
	v_and_b32 v53, v53, v210
	v_exp_f32 v62, v62
	v_exp_f32 v63, v63
	v_pk_add_f32 v[14:15], v[14:15], v[60:61]
	v_cvt_pk_bf16_f32 v54, v60, v61
	v_and_b32 v54, v54, v210
	v_pk_add_f32 v[14:15], v[14:15], v[62:63]
	v_cvt_pk_bf16_f32 v55, v62, v63
	v_and_b32 v55, v55, v210
	v_exp_f32 v64, v64
	s_waitcnt lgkmcnt(9)
	v_mfma_f32_32x32x16_bf16 v[80:95], v[162:165], v[120:123], v[80:95]
	ds_read_b64_tr_b16 v[154:155], v191 offset:2048
	ds_read_b64_tr_b16 v[156:157], v191 offset:3072
	v_exp_f32 v65, v65
	v_exp_f32 v66, v66
	v_exp_f32 v67, v67
	v_pk_add_f32 v[14:15], v[14:15], v[64:65]
	v_cvt_pk_bf16_f32 v64, v64, v65
	v_and_b32 v64, v64, v210
	v_exp_f32 v68, v68
	v_exp_f32 v69, v69
	v_pk_add_f32 v[14:15], v[14:15], v[66:67]
	v_cvt_pk_bf16_f32 v65, v66, v67
	v_and_b32 v65, v65, v210
	s_waitcnt lgkmcnt(10)
	v_mfma_f32_32x32x16_bf16 v[96:111], v[166:169], v[120:123], v[96:111]
	ds_write_b128 v200, v[6:9]
	ds_read_b64_tr_b16 v[158:159], v192 offset:2048
	ds_read_b64_tr_b16 v[160:161], v192 offset:3072
	v_exp_f32 v70, v70
	v_exp_f32 v71, v71
	v_pk_add_f32 v[14:15], v[14:15], v[68:69]
	v_cvt_pk_bf16_f32 v66, v68, v69
	v_and_b32 v66, v66, v210
	v_exp_f32 v72, v72
	v_exp_f32 v73, v73
	v_pk_add_f32 v[14:15], v[14:15], v[70:71]
	v_cvt_pk_bf16_f32 v67, v70, v71
	v_and_b32 v67, v67, v210
	s_waitcnt lgkmcnt(12)
	v_mfma_f32_32x32x16_bf16 v[80:95], v[170:173], v[124:127], v[80:95]
	ds_read_b64_tr_b16 v[162:163], v191 offset:4096
	ds_read_b64_tr_b16 v[164:165], v191 offset:5120
	v_exp_f32 v74, v74
	v_exp_f32 v75, v75
	v_pk_add_f32 v[14:15], v[14:15], v[72:73]
	v_cvt_pk_bf16_f32 v68, v72, v73
	v_and_b32 v68, v68, v210
	v_exp_f32 v76, v76
	v_exp_f32 v77, v77
	v_pk_add_f32 v[14:15], v[14:15], v[74:75]
	v_cvt_pk_bf16_f32 v69, v74, v75
	v_and_b32 v69, v69, v210
	v_exp_f32 v78, v78
	s_waitcnt lgkmcnt(12)
	v_mfma_f32_32x32x16_bf16 v[96:111], v[174:177], v[124:127], v[96:111]
	ds_write_b128 v200, v[136:139] offset:8192
	ds_read_b64_tr_b16 v[166:167], v192 offset:4096
	ds_read_b64_tr_b16 v[168:169], v192 offset:5120
	v_exp_f32 v79, v79
	v_pk_add_f32 v[14:15], v[14:15], v[76:77]
	v_cvt_pk_bf16_f32 v70, v76, v77
	v_and_b32 v70, v70, v210
	v_pk_add_f32 v[14:15], v[14:15], v[78:79]
	v_cvt_pk_bf16_f32 v71, v78, v79
	v_and_b32 v71, v71, v210
	v_add_f32 v188, v14, v15
	v_and_b32 v188, v188, v210
	v_add_f32 v206, v206, v188
	v_max_f32 v211, v211, v188
	s_cmp_eq_u32 s13, 2
	s_cselect_b32 s8, 0x19800, 0
	s_sub_u32 s8, 0x8800, s8
	s_add_u32 s13, s13, 1
	s_cmp_eq_u32 s13, 3
	s_cselect_b32 s13, 0, s13
	s_waitcnt lgkmcnt(0)
	s_add_u32 s9, s26, 2
	s_cmp_lt_u32 s9, s30
	s_cbranch_scc0 .Lat1_mid3
	global_load_dwordx4 v[2:5], v184, s[52:53]
	global_load_dwordx4 v[6:9], v184, s[52:53] offset:1024
	global_load_dwordx4 v[10:13], v185, s[52:53]
	global_load_dwordx4 v[136:139], v185, s[52:53] offset:1024
	s_add_u32 s52, s52, 0x100000
	s_addc_u32 s53, s53, 0
; template <int TYPE>
; __device__ __forceinline__ void attn_item(const Ctx& a, int b, int h, int qt, LAS unsigned char* lds) {
;     ...
;             float mx = -1e30f;
; #pragma unroll
;             for (int kb = 0; kb < 2; ++kb)
; #pragma unroll
;                 for (int r = 0; r < 16; ++r) mx = fmaxf(mx, s[sub][kb][r]);
;             mx = fmaxf(mx, __shfl_xor(mx, 32));
;             const float delta = mrun - mref;
;             const bool bump = (mx - delta) > 8.f;
;             const bool rare = __builtin_amdgcn_ballot_w64(bump || delta != 0.f) != 0ull;
;             float fpost = 1.f;
;             if (rare) {
;                 const float mnew = bump ? mref + mx : mrun;
;                 const float pre = __builtin_amdgcn_exp2f(delta);
;                 fpost = __builtin_amdgcn_exp2f(mref - mnew);
;                 mrun = mnew;
;                 lrun *= pre;
; #pragma unroll
;                 for (int db = 0; db < 2; ++db)
; #pragma unroll
;                     for (int r = 0; r < 16; ++r) oacc[db][r] *= pre;
;             }
;             float ps = 0.f;
; #pragma unroll
;             for (int kb = 0; kb < 2; ++kb)
; #pragma unroll
;                 for (int r = 0; r < 16; ++r) { float p = __builtin_amdgcn_exp2f(s[sub][kb][r]); s[sub][kb][r] = p; ps += p; }
;             lrun += ps;
; #pragma unroll
;             for (int kb = 0; kb < 2; ++kb)
; #pragma unroll
;                 for (int c = 0; c < 2; ++c) {
;                     bf16x8 pb = pack8(s[sub][kb], c);
; #pragma unroll
;                     for (int db = 0; db < 2; ++db)
;                         oacc[db] = __builtin_amdgcn_mfma_f32_32x32x16_bf16(lds_a2(VT + (db * 32 + l32) * VLD + sub * 64 + kb * 32 + c * 16 + hb * 4), pb, oacc[db], 0, 0, 0);
;                 }
;             if (rare) {
;                 lrun *= fpost;
; #pragma unroll
;                 for (int db = 0; db < 2; ++db)
; #pragma unroll
;                     for (int r = 0; r < 16; ++r) oacc[db][r] *= fpost;
;             }
;         }
.Lat1_mid3:
	v_add_u32 v193, s8, v193
	v_add_u32 v200, s8, v200
	s_barrier
	s_nop 7
	s_nop 0
	v_mfma_f32_32x32x16_bf16 v[16:31], v[146:149], v[48:51], v[16:31]
	ds_read_b64_tr_b16 v[170:171], v191 offset:6144
	ds_read_b64_tr_b16 v[172:173], v191 offset:7168
	v_exp_f32 v80, v80
	v_exp_f32 v81, v81
	v_exp_f32 v82, v82
	v_exp_f32 v83, v83
	v_mov_b32 v14, v80
	v_mov_b32 v15, v81
	v_cvt_pk_bf16_f32 v80, v80, v81
	v_and_b32 v80, v80, v210
	v_exp_f32 v84, v84
	v_exp_f32 v85, v85
	v_mfma_f32_32x32x16_bf16 v[32:47], v[150:153], v[48:51], v[32:47]
	ds_read_b64_tr_b16 v[174:175], v192 offset:6144
	ds_read_b64_tr_b16 v[176:177], v192 offset:7168
	v_pk_add_f32 v[14:15], v[14:15], v[82:83]
	v_cvt_pk_bf16_f32 v81, v82, v83
	v_and_b32 v81, v81, v210
	v_exp_f32 v86, v86
	v_exp_f32 v87, v87
	v_pk_add_f32 v[14:15], v[14:15], v[84:85]
	v_cvt_pk_bf16_f32 v82, v84, v85
	v_and_b32 v82, v82, v210
	v_exp_f32 v88, v88
	v_exp_f32 v89, v89
	v_pk_add_f32 v[14:15], v[14:15], v[86:87]
	v_mfma_f32_32x32x16_bf16 v[16:31], v[154:157], v[52:55], v[16:31]
	ds_read_b64_tr_b16 v[146:147], v191 offset:8192
	ds_read_b64_tr_b16 v[148:149], v191 offset:9216
	v_cvt_pk_bf16_f32 v83, v86, v87
	v_and_b32 v83, v83, v210
	v_exp_f32 v90, v90
	v_exp_f32 v91, v91
	v_pk_add_f32 v[14:15], v[14:15], v[88:89]
	v_cvt_pk_bf16_f32 v84, v88, v89
	v_and_b32 v84, v84, v210
	v_exp_f32 v92, v92
	v_exp_f32 v93, v93
	v_pk_add_f32 v[14:15], v[14:15], v[90:91]
	v_mfma_f32_32x32x16_bf16 v[32:47], v[158:161], v[52:55], v[32:47]
	ds_read_b64_tr_b16 v[150:151], v192 offset:8192
	ds_read_b64_tr_b16 v[152:153], v192 offset:9216
	v_cvt_pk_bf16_f32 v85, v90, v91
	v_and_b32 v85, v85, v210
	v_exp_f32 v94, v94
	v_exp_f32 v95, v95
	v_pk_add_f32 v[14:15], v[14:15], v[92:93]
	v_cvt_pk_bf16_f32 v86, v92, v93
	v_and_b32 v86, v86, v210
	v_pk_add_f32 v[14:15], v[14:15], v[94:95]
	v_cvt_pk_bf16_f32 v87, v94, v95
	v_and_b32 v87, v87, v210
	v_exp_f32 v96, v96
	v_mfma_f32_32x32x16_bf16 v[16:31], v[162:165], v[64:67], v[16:31]
	ds_read_b64_tr_b16 v[154:155], v191 offset:10240
	ds_read_b64_tr_b16 v[156:157], v191 offset:11264
	v_exp_f32 v97, v97
	v_exp_f32 v98, v98
	v_exp_f32 v99, v99
	v_pk_add_f32 v[14:15], v[14:15], v[96:97]
	v_cvt_pk_bf16_f32 v96, v96, v97
	v_and_b32 v96, v96, v210
	v_exp_f32 v100, v100
	v_exp_f32 v101, v101
	v_pk_add_f32 v[14:15], v[14:15], v[98:99]
	v_cvt_pk_bf16_f32 v97, v98, v99
	v_and_b32 v97, v97, v210
	v_mfma_f32_32x32x16_bf16 v[32:47], v[166:169], v[64:67], v[32:47]
	ds_read_b64_tr_b16 v[158:159], v192 offset:10240
	ds_read_b64_tr_b16 v[160:161], v192 offset:11264
	v_exp_f32 v102, v102
	v_exp_f32 v103, v103
	v_pk_add_f32 v[14:15], v[14:15], v[100:101]
	v_cvt_pk_bf16_f32 v98, v100, v101
	v_and_b32 v98, v98, v210
	v_exp_f32 v104, v104
	v_exp_f32 v105, v105
	v_pk_add_f32 v[14:15], v[14:15], v[102:103]
	v_cvt_pk_bf16_f32 v99, v102, v103
	v_and_b32 v99, v99, v210
	s_waitcnt lgkmcnt(10)
	v_mfma_f32_32x32x16_bf16 v[16:31], v[170:173], v[68:71], v[16:31]
	ds_read_b64_tr_b16 v[162:163], v191 offset:12288
	ds_read_b64_tr_b16 v[164:165], v191 offset:13312
	v_exp_f32 v106, v106
	v_exp_f32 v107, v107
	v_pk_add_f32 v[14:15], v[14:15], v[104:105]
	v_cvt_pk_bf16_f32 v100, v104, v105
	v_and_b32 v100, v100, v210
	v_exp_f32 v108, v108
	v_exp_f32 v109, v109
	v_pk_add_f32 v[14:15], v[14:15], v[106:107]
	v_cvt_pk_bf16_f32 v101, v106, v107
	v_and_b32 v101, v101, v210
	v_exp_f32 v110, v110
	s_waitcnt lgkmcnt(10)
	v_mfma_f32_32x32x16_bf16 v[32:47], v[174:177], v[68:71], v[32:47]
	ds_read_b64_tr_b16 v[166:167], v192 offset:12288
	ds_read_b64_tr_b16 v[168:169], v192 offset:13312
	v_exp_f32 v111, v111
	v_pk_add_f32 v[14:15], v[14:15], v[108:109]
	v_cvt_pk_bf16_f32 v102, v108, v109
	v_and_b32 v102, v102, v210
	v_pk_add_f32 v[14:15], v[14:15], v[110:111]
	v_cvt_pk_bf16_f32 v103, v110, v111
	v_and_b32 v103, v103, v210
	v_add_f32 v188, v14, v15
	v_and_b32 v188, v188, v210
	v_add_f32 v206, v206, v188
	v_max_f32 v211, v211, v188
	s_waitcnt lgkmcnt(10)
	v_mfma_f32_32x32x16_bf16 v[16:31], v[146:149], v[80:83], v[16:31]
	ds_read_b64_tr_b16 v[170:171], v191 offset:14336
	ds_read_b64_tr_b16 v[172:173], v191 offset:15360
	s_waitcnt lgkmcnt(10)
	v_mfma_f32_32x32x16_bf16 v[32:47], v[150:153], v[80:83], v[32:47]
	ds_read_b64_tr_b16 v[174:175], v192 offset:14336
	ds_read_b64_tr_b16 v[176:177], v192 offset:15360
	s_waitcnt lgkmcnt(10)
	v_mfma_f32_32x32x16_bf16 v[16:31], v[154:157], v[84:87], v[16:31]
	s_waitcnt lgkmcnt(8)
	v_mfma_f32_32x32x16_bf16 v[32:47], v[158:161], v[84:87], v[32:47]
	s_waitcnt lgkmcnt(6)
	v_mfma_f32_32x32x16_bf16 v[16:31], v[162:165], v[96:99], v[16:31]
	s_waitcnt lgkmcnt(4)
	v_mfma_f32_32x32x16_bf16 v[32:47], v[166:169], v[96:99], v[32:47]
	s_waitcnt lgkmcnt(2)
	v_mfma_f32_32x32x16_bf16 v[16:31], v[170:173], v[100:103], v[16:31]
	s_waitcnt lgkmcnt(0)
	v_mfma_f32_32x32x16_bf16 v[32:47], v[174:177], v[100:103], v[32:47]
	v_cmp_lt_f32 vcc, 0x47800000, v211
	s_cmp_lg_u64 vcc, 0
	s_cbranch_scc0 .Lat1_pairend
	v_mov_b32 v1, v211
	s_nop 1
	v_permlane32_swap_b32 v1, v211
	v_max_f32 v1, v1, v211
	v_cmp_lt_f32 vcc, 0x47800000, v1
	v_log_f32 v1, v1
	s_nop 0
	v_cndmask_b32 v14, v205, v1, vcc
	v_sub_f32 v15, v205, v14
	v_exp_f32 v15, v15
	v_mov_b32 v205, v14
	v_add_f32 v207, 0x41000000, v14
	v_mul_f32 v16, v16, v15
	v_mul_f32 v17, v17, v15
	v_mul_f32 v18, v18, v15
	v_mul_f32 v19, v19, v15
	v_mul_f32 v20, v20, v15
	v_mul_f32 v21, v21, v15
	v_mul_f32 v22, v22, v15
	v_mul_f32 v23, v23, v15
	v_mul_f32 v24, v24, v15
	v_mul_f32 v25, v25, v15
	v_mul_f32 v26, v26, v15
	v_mul_f32 v27, v27, v15
	v_mul_f32 v28, v28, v15
	v_mul_f32 v29, v29, v15
	v_mul_f32 v30, v30, v15
	v_mul_f32 v31, v31, v15
	v_mul_f32 v32, v32, v15
	v_mul_f32 v33, v33, v15
	v_mul_f32 v34, v34, v15
	v_mul_f32 v35, v35, v15
	v_mul_f32 v36, v36, v15
	v_mul_f32 v37, v37, v15
	v_mul_f32 v38, v38, v15
	v_mul_f32 v39, v39, v15
	v_mul_f32 v40, v40, v15
	v_mul_f32 v41, v41, v15
	v_mul_f32 v42, v42, v15
	v_mul_f32 v43, v43, v15
	v_mul_f32 v44, v44, v15
	v_mul_f32 v45, v45, v15
	v_mul_f32 v46, v46, v15
	v_mul_f32 v47, v47, v15
	v_mul_f32 v206, v206, v15
	v_cmp_neq_f32_e64 s[36:37], 0, v205
	s_branch .Lat1_pairend
